# flat grid barrier: one no-return arrival atomic per workgroup on its XCC counter, all workgroups poll the sum of the 16 counters (no leader relay, no L2 write-back)
# baseline (speedup 1.0000x reference)
.LBB0_575:
	v_readlane_b32 s4, v251, 10
	v_readlane_b32 s5, v251, 11
	v_readlane_b32 s6, v250, 0
	s_waitcnt vmcnt(0) expcnt(0) lgkmcnt(0)
	s_nop 4
	global_atomic_add v131, v220, s[4:5] sc1
	v_mov_b32_e32 v1, s6
	ds_read_b32 v2, v1
	v_readlane_b32 s4, v251, 14
	v_readlane_b32 s5, v251, 15
	s_waitcnt lgkmcnt(0)
	v_add_u32_e32 v2, 1, v2
	s_nop 1
	ds_write_b32 v1, v2
	v_readfirstlane_b32 s6, v2
	s_nop 3
	v_readlane_b32 s8, v250, 1
	v_readlane_b32 s9, v250, 2
	s_nop 3
	s_load_dword s8, s[8:9], 0x0
	s_waitcnt lgkmcnt(0)
	s_mul_i32 s6, s6, s8
	s_sub_u32 s4, s4, 0x2000
	s_subb_u32 s5, s5, 0
	s_mov_b64 exec, 0xffff
	v_mbcnt_lo_u32_b32 v1, -1, 0
	v_lshlrev_b32_e32 v1, 8, v1
	s_mov_b32 s7, 0
	s_nop 4
.Lxbar_poll:
	global_load_dword v2, v1, s[4:5] sc1
	s_waitcnt vmcnt(0)
	s_nop 1
	v_add_u32_dpp v2, v2, v2 quad_perm:[1,0,3,2] row_mask:0xf bank_mask:0xf bound_ctrl:1
	s_nop 1
	v_add_u32_dpp v2, v2, v2 quad_perm:[2,3,0,1] row_mask:0xf bank_mask:0xf bound_ctrl:1
	s_nop 1
	v_add_u32_dpp v2, v2, v2 row_half_mirror row_mask:0xf bank_mask:0xf bound_ctrl:1
	s_nop 1
	v_add_u32_dpp v2, v2, v2 row_mirror row_mask:0xf bank_mask:0xf bound_ctrl:1
	s_nop 1
	v_readfirstlane_b32 s8, v2
	s_add_i32 s7, s7, 1
	s_nop 3
	s_cmp_ge_u32 s8, s6
	s_cbranch_scc1 .Lxbar_done
	s_sleep 1
	s_cmp_lt_u32 s7, 0x4000
	s_cbranch_scc1 .Lxbar_poll
.Lxbar_done:
	buffer_inv sc1
	s_waitcnt vmcnt(0)
	s_getpc_b64 s[98:99]
